# Wout residual GEMM also on the 256x128 block tile (two 64-row epilogue halves)
# speedup vs baseline: 1.5889x; 1.0021x over previous
.LBB0_600:
	s_waitcnt lgkmcnt(0)
	s_lshr_b32 s0, s11, 6
	s_lshl_b32 s0, s0, 3
	s_and_b32 s4, s11, 7
	s_or_b32 s0, s0, s4
	s_lshl_b32 s0, s0, 8
	s_bfe_u32 s14, s11, 0x30003
	s_lshl_b32 s14, s14, 7
	v_lshrrev_b32_e32 v132, 4, v182
	v_xor_b32_e32 v132, v132, v182
	v_and_b32_e32 v132, 7, v132
	v_lshlrev_b32_e32 v132, 4, v132
	v_lshrrev_b32_e32 v133, 3, v182
	v_lshrrev_b32_e32 v134, 6, v182
	v_mul_u32_u24_e32 v180, 0x1900, v133
	v_readfirstlane_b32 s5, v134
	v_add_u32_e32 v180, v180, v132
	v_lshl_add_u32 v248, v133, 11, v132
	v_and_b32_e32 v135, 15, v182
	v_bfe_u32 v136, v182, 4, 2
	v_bfe_u32 v137, v182, 1, 3
	v_xor_b32_e32 v138, v136, v137
	v_or_b32_e32 v139, 4, v136
	v_xor_b32_e32 v139, v139, v137
	v_lshlrev_b32_e32 v138, 4, v138
	v_lshlrev_b32_e32 v139, 4, v139
	v_lshl_or_b32 v138, v135, 7, v138
	v_lshl_or_b32 v139, v135, 7, v139
	v_bfe_u32 v140, v182, 7, 1
	v_bfe_u32 v141, v182, 6, 1
	v_lshl_add_u32 v181, v140, 14, v138
	v_lshl_add_u32 v208, v140, 14, v139
	v_lshl_add_u32 v223, v141, 13, v138
	v_lshl_add_u32 v233, v141, 13, v139
	s_lshl_b32 s5, s5, 10
	s_mul_hi_u32 s15, s0, 0x1900
	s_mul_i32 s4, s0, 0x1900
	v_readlane_b32 s8, v250, 13
	v_readlane_b32 s9, v250, 14
	s_add_u32 s8, s8, s4
	s_addc_u32 s9, s9, s15
	s_mul_hi_u32 s15, s14, 0x800
	s_mul_i32 s4, s14, 0x800
	v_readlane_b32 s12, v250, 15
	v_readlane_b32 s13, v250, 16
	s_add_u32 s12, s12, s4
	s_addc_u32 s13, s13, s15
	s_mov_b32 s23, 0x8000
	s_add_u32 m0, s5, 0x0
	s_nop 0
	global_load_lds_dwordx4 v180, s[8:9]
	s_add_u32 m0, s5, 0x1000
	s_add_u32 s20, s8, 0x32000
	s_addc_u32 s21, s9, 0
	global_load_lds_dwordx4 v180, s[20:21]
	s_add_u32 m0, s5, 0x2000
	s_add_u32 s20, s8, 0x64000
	s_addc_u32 s21, s9, 0
	global_load_lds_dwordx4 v180, s[20:21]
	s_add_u32 m0, s5, 0x3000
	s_add_u32 s20, s8, 0x96000
	s_addc_u32 s21, s9, 0
	global_load_lds_dwordx4 v180, s[20:21]
	s_add_u32 m0, s5, 0x4000
	s_add_u32 s20, s8, 0xc8000
	s_addc_u32 s21, s9, 0
	global_load_lds_dwordx4 v180, s[20:21]
	s_add_u32 m0, s5, 0x5000
	s_add_u32 s20, s8, 0xfa000
	s_addc_u32 s21, s9, 0
	global_load_lds_dwordx4 v180, s[20:21]
	s_add_u32 m0, s5, 0x6000
	s_add_u32 s20, s8, 0x12c000
	s_addc_u32 s21, s9, 0
	global_load_lds_dwordx4 v180, s[20:21]
	s_add_u32 m0, s5, 0x7000
	s_add_u32 s20, s8, 0x15e000
	s_addc_u32 s21, s9, 0
	global_load_lds_dwordx4 v180, s[20:21]
	s_add_u32 s8, s8, 0x80
	s_addc_u32 s9, s9, 0
	s_add_u32 m0, s5, s23
	s_nop 0
	global_load_lds_dwordx4 v248, s[12:13]
	s_add_u32 m0, m0, 0x1000
	s_add_u32 s20, s12, 0x10000
	s_addc_u32 s21, s13, 0
	global_load_lds_dwordx4 v248, s[20:21]
	s_add_u32 m0, m0, 0x1000
	s_add_u32 s20, s12, 0x20000
	s_addc_u32 s21, s13, 0
	global_load_lds_dwordx4 v248, s[20:21]
	s_add_u32 m0, m0, 0x1000
	s_add_u32 s20, s12, 0x30000
	s_addc_u32 s21, s13, 0
	global_load_lds_dwordx4 v248, s[20:21]
	s_add_u32 s12, s12, 0x80
	s_addc_u32 s13, s13, 0
	v_mov_b32_e32 v0, 0
	v_mov_b32_e32 v1, v0
	v_mov_b32_e32 v2, v0
	v_mov_b32_e32 v3, v0
	v_mov_b32_e32 v4, v0
	v_mov_b32_e32 v5, v0
	v_mov_b32_e32 v6, v0
	v_mov_b32_e32 v7, v0
	v_mov_b32_e32 v8, v0
	v_mov_b32_e32 v9, v0
	v_mov_b32_e32 v10, v0
	v_mov_b32_e32 v11, v0
	v_mov_b32_e32 v12, v0
	v_mov_b32_e32 v13, v0
	v_mov_b32_e32 v14, v0
	v_mov_b32_e32 v15, v0
	v_mov_b32_e32 v16, v0
	v_mov_b32_e32 v17, v0
	v_mov_b32_e32 v18, v0
	v_mov_b32_e32 v19, v0
	v_mov_b32_e32 v20, v0
	v_mov_b32_e32 v21, v0
	v_mov_b32_e32 v22, v0
	v_mov_b32_e32 v23, v0
	v_mov_b32_e32 v24, v0
	v_mov_b32_e32 v25, v0
	v_mov_b32_e32 v26, v0
	v_mov_b32_e32 v27, v0
	v_mov_b32_e32 v28, v0
	v_mov_b32_e32 v29, v0
	v_mov_b32_e32 v30, v0
	v_mov_b32_e32 v31, v0
	v_mov_b32_e32 v32, v0
	v_mov_b32_e32 v33, v0
	v_mov_b32_e32 v34, v0
	v_mov_b32_e32 v35, v0
	v_mov_b32_e32 v36, v0
	v_mov_b32_e32 v37, v0
	v_mov_b32_e32 v38, v0
	v_mov_b32_e32 v39, v0
	v_mov_b32_e32 v40, v0
	v_mov_b32_e32 v41, v0
	v_mov_b32_e32 v42, v0
	v_mov_b32_e32 v43, v0
	v_mov_b32_e32 v44, v0
	v_mov_b32_e32 v45, v0
	v_mov_b32_e32 v46, v0
	v_mov_b32_e32 v47, v0
	v_mov_b32_e32 v48, v0
	v_mov_b32_e32 v49, v0
	v_mov_b32_e32 v50, v0
	v_mov_b32_e32 v51, v0
	v_mov_b32_e32 v52, v0
	v_mov_b32_e32 v53, v0
	v_mov_b32_e32 v54, v0
	v_mov_b32_e32 v55, v0
	v_mov_b32_e32 v56, v0
	v_mov_b32_e32 v57, v0
	v_mov_b32_e32 v58, v0
	v_mov_b32_e32 v59, v0
	v_mov_b32_e32 v60, v0
	v_mov_b32_e32 v61, v0
	v_mov_b32_e32 v62, v0
	v_mov_b32_e32 v63, v0
	v_mov_b32_e32 v64, v0
	v_mov_b32_e32 v65, v0
	v_mov_b32_e32 v66, v0
	v_mov_b32_e32 v67, v0
	v_mov_b32_e32 v68, v0
	v_mov_b32_e32 v69, v0
	v_mov_b32_e32 v70, v0
	v_mov_b32_e32 v71, v0
	v_mov_b32_e32 v72, v0
	v_mov_b32_e32 v73, v0
	v_mov_b32_e32 v74, v0
	v_mov_b32_e32 v75, v0
	v_mov_b32_e32 v76, v0
	v_mov_b32_e32 v77, v0
	v_mov_b32_e32 v78, v0
	v_mov_b32_e32 v79, v0
	v_mov_b32_e32 v80, v0
	v_mov_b32_e32 v81, v0
	v_mov_b32_e32 v82, v0
	v_mov_b32_e32 v83, v0
	v_mov_b32_e32 v84, v0
	v_mov_b32_e32 v85, v0
	v_mov_b32_e32 v86, v0
	v_mov_b32_e32 v87, v0
	v_mov_b32_e32 v88, v0
	v_mov_b32_e32 v89, v0
	v_mov_b32_e32 v90, v0
	v_mov_b32_e32 v91, v0
	v_mov_b32_e32 v92, v0
	v_mov_b32_e32 v93, v0
	v_mov_b32_e32 v94, v0
	v_mov_b32_e32 v95, v0
	v_mov_b32_e32 v96, v0
	v_mov_b32_e32 v97, v0
	v_mov_b32_e32 v98, v0
	v_mov_b32_e32 v99, v0
	v_mov_b32_e32 v100, v0
	v_mov_b32_e32 v101, v0
	v_mov_b32_e32 v102, v0
	v_mov_b32_e32 v103, v0
	v_mov_b32_e32 v104, v0
	v_mov_b32_e32 v105, v0
	v_mov_b32_e32 v106, v0
	v_mov_b32_e32 v107, v0
	v_mov_b32_e32 v108, v0
	v_mov_b32_e32 v109, v0
	v_mov_b32_e32 v110, v0
	v_mov_b32_e32 v111, v0
	v_mov_b32_e32 v116, v0
	v_mov_b32_e32 v117, v0
	v_mov_b32_e32 v118, v0
	v_mov_b32_e32 v119, v0
	v_mov_b32_e32 v120, v0
	v_mov_b32_e32 v121, v0
	v_mov_b32_e32 v122, v0
	v_mov_b32_e32 v123, v0
	v_mov_b32_e32 v124, v0
	v_mov_b32_e32 v125, v0
	v_mov_b32_e32 v126, v0
	v_mov_b32_e32 v127, v0
	v_mov_b32_e32 v128, v0
	v_mov_b32_e32 v129, v0
	v_mov_b32_e32 v130, v0
	v_mov_b32_e32 v131, v0
	s_movk_i32 s16, 15
.Lg4_r2:
	s_waitcnt vmcnt(0)
	s_barrier
	s_xor_b32 s23, s23, 0x4000
	s_cmp_eq_u32 s16, 0
	s_cbranch_scc1 .Lg4_r2_nb
	s_add_u32 m0, s5, s23
	s_nop 0
	global_load_lds_dwordx4 v248, s[12:13]
	s_add_u32 m0, m0, 0x1000
	s_add_u32 s20, s12, 0x10000
	s_addc_u32 s21, s13, 0
	global_load_lds_dwordx4 v248, s[20:21]
	s_add_u32 m0, m0, 0x1000
	s_add_u32 s20, s12, 0x20000
	s_addc_u32 s21, s13, 0
	global_load_lds_dwordx4 v248, s[20:21]
	s_add_u32 m0, m0, 0x1000
	s_add_u32 s20, s12, 0x30000
	s_addc_u32 s21, s13, 0
	global_load_lds_dwordx4 v248, s[20:21]
	s_add_u32 s12, s12, 0x80
	s_addc_u32 s13, s13, 0
.Lg4_r2_nb:
	ds_read_b128 v[132:135], v181 offset:0
	ds_read_b128 v[136:139], v181 offset:2048
	ds_read_b128 v[140:143], v181 offset:4096
	ds_read_b128 v[144:147], v181 offset:6144
	ds_read_b128 v[148:151], v181 offset:8192
	ds_read_b128 v[152:155], v181 offset:10240
	ds_read_b128 v[156:159], v181 offset:12288
	ds_read_b128 v[160:163], v181 offset:14336
	ds_read_b128 v[164:167], v208 offset:0
	ds_read_b128 v[168:171], v208 offset:2048
	ds_read_b128 v[172:175], v208 offset:4096
	ds_read_b128 v[176:179], v208 offset:6144
	ds_read_b128 v[224:227], v208 offset:8192
	ds_read_b128 v[228:231], v208 offset:10240
	s_waitcnt lgkmcnt(6)
	ds_read_b128 v[234:237], v208 offset:12288
	ds_read_b128 v[238:241], v208 offset:14336
	ds_read_b128 v[242:245], v223 offset:32768
	ds_read_b128 v[112:115], v223 offset:34816
	s_waitcnt lgkmcnt(2)
	s_barrier
	s_cmp_eq_u32 s16, 0
	s_cbranch_scc1 .Lg4_r2_nl
	s_add_u32 m0, s5, 0x0
	s_nop 0
	global_load_lds_dwordx4 v180, s[8:9]
	s_add_u32 m0, s5, 0x1000
	s_add_u32 s20, s8, 0x32000
	s_addc_u32 s21, s9, 0
	global_load_lds_dwordx4 v180, s[20:21]
	s_add_u32 m0, s5, 0x2000
	s_add_u32 s20, s8, 0x64000
	s_addc_u32 s21, s9, 0
	global_load_lds_dwordx4 v180, s[20:21]
	s_add_u32 m0, s5, 0x3000
	s_add_u32 s20, s8, 0x96000
	s_addc_u32 s21, s9, 0
	global_load_lds_dwordx4 v180, s[20:21]
	s_add_u32 m0, s5, 0x4000
	s_add_u32 s20, s8, 0xc8000
	s_addc_u32 s21, s9, 0
	global_load_lds_dwordx4 v180, s[20:21]
	s_add_u32 m0, s5, 0x5000
	s_add_u32 s20, s8, 0xfa000
	s_addc_u32 s21, s9, 0
	global_load_lds_dwordx4 v180, s[20:21]
	s_add_u32 m0, s5, 0x6000
	s_add_u32 s20, s8, 0x12c000
	s_addc_u32 s21, s9, 0
	global_load_lds_dwordx4 v180, s[20:21]
	s_add_u32 m0, s5, 0x7000
	s_add_u32 s20, s8, 0x15e000
	s_addc_u32 s21, s9, 0
	global_load_lds_dwordx4 v180, s[20:21]
	s_add_u32 s8, s8, 0x80
	s_addc_u32 s9, s9, 0
.Lg4_r2_nl:
	s_waitcnt lgkmcnt(1)
	v_mfma_f32_16x16x32_f16 v[0:3], v[132:135], v[242:245], v[0:3]
	v_mfma_f32_16x16x32_f16 v[16:19], v[136:139], v[242:245], v[16:19]
	v_mfma_f32_16x16x32_f16 v[32:35], v[140:143], v[242:245], v[32:35]
	v_mfma_f32_16x16x32_f16 v[48:51], v[144:147], v[242:245], v[48:51]
	v_mfma_f32_16x16x32_f16 v[64:67], v[148:151], v[242:245], v[64:67]
	v_mfma_f32_16x16x32_f16 v[80:83], v[152:155], v[242:245], v[80:83]
	v_mfma_f32_16x16x32_f16 v[96:99], v[156:159], v[242:245], v[96:99]
	v_mfma_f32_16x16x32_f16 v[116:119], v[160:163], v[242:245], v[116:119]
	ds_read_b128 v[242:245], v223 offset:36864
	s_waitcnt lgkmcnt(1)
	v_mfma_f32_16x16x32_f16 v[4:7], v[132:135], v[112:115], v[4:7]
	v_mfma_f32_16x16x32_f16 v[20:23], v[136:139], v[112:115], v[20:23]
	v_mfma_f32_16x16x32_f16 v[36:39], v[140:143], v[112:115], v[36:39]
	v_mfma_f32_16x16x32_f16 v[52:55], v[144:147], v[112:115], v[52:55]
	v_mfma_f32_16x16x32_f16 v[68:71], v[148:151], v[112:115], v[68:71]
	v_mfma_f32_16x16x32_f16 v[84:87], v[152:155], v[112:115], v[84:87]
	v_mfma_f32_16x16x32_f16 v[100:103], v[156:159], v[112:115], v[100:103]
	v_mfma_f32_16x16x32_f16 v[120:123], v[160:163], v[112:115], v[120:123]
	ds_read_b128 v[112:115], v223 offset:38912
	s_waitcnt lgkmcnt(1)
	v_mfma_f32_16x16x32_f16 v[8:11], v[132:135], v[242:245], v[8:11]
	v_mfma_f32_16x16x32_f16 v[24:27], v[136:139], v[242:245], v[24:27]
	v_mfma_f32_16x16x32_f16 v[40:43], v[140:143], v[242:245], v[40:43]
	v_mfma_f32_16x16x32_f16 v[56:59], v[144:147], v[242:245], v[56:59]
	v_mfma_f32_16x16x32_f16 v[72:75], v[148:151], v[242:245], v[72:75]
	v_mfma_f32_16x16x32_f16 v[88:91], v[152:155], v[242:245], v[88:91]
	v_mfma_f32_16x16x32_f16 v[104:107], v[156:159], v[242:245], v[104:107]
	v_mfma_f32_16x16x32_f16 v[124:127], v[160:163], v[242:245], v[124:127]
	ds_read_b128 v[242:245], v233 offset:32768
	s_waitcnt lgkmcnt(1)
	v_mfma_f32_16x16x32_f16 v[12:15], v[132:135], v[112:115], v[12:15]
	v_mfma_f32_16x16x32_f16 v[28:31], v[136:139], v[112:115], v[28:31]
	v_mfma_f32_16x16x32_f16 v[44:47], v[140:143], v[112:115], v[44:47]
	v_mfma_f32_16x16x32_f16 v[60:63], v[144:147], v[112:115], v[60:63]
	v_mfma_f32_16x16x32_f16 v[76:79], v[148:151], v[112:115], v[76:79]
	v_mfma_f32_16x16x32_f16 v[92:95], v[152:155], v[112:115], v[92:95]
	v_mfma_f32_16x16x32_f16 v[108:111], v[156:159], v[112:115], v[108:111]
	v_mfma_f32_16x16x32_f16 v[128:131], v[160:163], v[112:115], v[128:131]
	ds_read_b128 v[112:115], v233 offset:34816
	s_waitcnt lgkmcnt(1)
	v_mfma_f32_16x16x32_f16 v[0:3], v[164:167], v[242:245], v[0:3]
	v_mfma_f32_16x16x32_f16 v[16:19], v[168:171], v[242:245], v[16:19]
	v_mfma_f32_16x16x32_f16 v[32:35], v[172:175], v[242:245], v[32:35]
	v_mfma_f32_16x16x32_f16 v[48:51], v[176:179], v[242:245], v[48:51]
	v_mfma_f32_16x16x32_f16 v[64:67], v[224:227], v[242:245], v[64:67]
	v_mfma_f32_16x16x32_f16 v[80:83], v[228:231], v[242:245], v[80:83]
	v_mfma_f32_16x16x32_f16 v[96:99], v[234:237], v[242:245], v[96:99]
	v_mfma_f32_16x16x32_f16 v[116:119], v[238:241], v[242:245], v[116:119]
	ds_read_b128 v[242:245], v233 offset:36864
	s_waitcnt lgkmcnt(1)
	v_mfma_f32_16x16x32_f16 v[4:7], v[164:167], v[112:115], v[4:7]
	v_mfma_f32_16x16x32_f16 v[20:23], v[168:171], v[112:115], v[20:23]
	v_mfma_f32_16x16x32_f16 v[36:39], v[172:175], v[112:115], v[36:39]
	v_mfma_f32_16x16x32_f16 v[52:55], v[176:179], v[112:115], v[52:55]
	v_mfma_f32_16x16x32_f16 v[68:71], v[224:227], v[112:115], v[68:71]
	v_mfma_f32_16x16x32_f16 v[84:87], v[228:231], v[112:115], v[84:87]
	v_mfma_f32_16x16x32_f16 v[100:103], v[234:237], v[112:115], v[100:103]
	v_mfma_f32_16x16x32_f16 v[120:123], v[238:241], v[112:115], v[120:123]
	ds_read_b128 v[112:115], v233 offset:38912
	s_waitcnt lgkmcnt(1)
	v_mfma_f32_16x16x32_f16 v[8:11], v[164:167], v[242:245], v[8:11]
	v_mfma_f32_16x16x32_f16 v[24:27], v[168:171], v[242:245], v[24:27]
	v_mfma_f32_16x16x32_f16 v[40:43], v[172:175], v[242:245], v[40:43]
	v_mfma_f32_16x16x32_f16 v[56:59], v[176:179], v[242:245], v[56:59]
	v_mfma_f32_16x16x32_f16 v[72:75], v[224:227], v[242:245], v[72:75]
	v_mfma_f32_16x16x32_f16 v[88:91], v[228:231], v[242:245], v[88:91]
	v_mfma_f32_16x16x32_f16 v[104:107], v[234:237], v[242:245], v[104:107]
	v_mfma_f32_16x16x32_f16 v[124:127], v[238:241], v[242:245], v[124:127]
	s_waitcnt lgkmcnt(0)
	v_mfma_f32_16x16x32_f16 v[12:15], v[164:167], v[112:115], v[12:15]
	v_mfma_f32_16x16x32_f16 v[28:31], v[168:171], v[112:115], v[28:31]
	v_mfma_f32_16x16x32_f16 v[44:47], v[172:175], v[112:115], v[44:47]
	v_mfma_f32_16x16x32_f16 v[60:63], v[176:179], v[112:115], v[60:63]
	v_mfma_f32_16x16x32_f16 v[76:79], v[224:227], v[112:115], v[76:79]
	v_mfma_f32_16x16x32_f16 v[92:95], v[228:231], v[112:115], v[92:95]
	v_mfma_f32_16x16x32_f16 v[108:111], v[234:237], v[112:115], v[108:111]
	v_mfma_f32_16x16x32_f16 v[128:131], v[238:241], v[112:115], v[128:131]
	v_xor_b32_e32 v223, 0x4000, v223
	v_xor_b32_e32 v233, 0x4000, v233
	s_sub_u32 s16, s16, 1
	s_cmp_lg_u32 s16, -1
	s_cbranch_scc1 .Lg4_r2
	s_nop 7
	v_bfe_u32 v208, v182, 7, 1
	v_bfe_u32 v223, v182, 4, 2
	v_lshlrev_b32_e32 v223, 2, v223
	v_lshl_or_b32 v208, v208, 7, v223
	v_add_u32_e32 v180, s0, v208
	v_bfe_u32 v208, v182, 6, 1
	v_and_b32_e32 v223, 15, v182
	v_lshl_or_b32 v208, v208, 6, v223
	v_add_u32_e32 v208, s14, v208
	v_lshlrev_b32_e32 v181, 2, v208
	s_lshr_b32 s4, s0, 13
	s_add_i32 s4, s4, s10
	s_mul_hi_i32 s9, s4, 0x9000
	s_mul_i32 s8, s4, 0x9000
	s_add_u32 s8, s50, s8
	s_addc_u32 s9, s51, s9
	s_add_u32 s8, s8, 0x5000
	s_addc_u32 s9, s9, 0
	v_mov_b32_e32 v247, s9
	v_add_co_u32_e32 v246, vcc, s8, v181
	s_nop 1
	v_addc_co_u32_e32 v247, vcc, 0, v247, vcc
	v_lshl_add_u32 v164, v180, 12, v181
	v_add_u32_e32 v165, 0x1000, v164
	v_add_u32_e32 v166, 0x3000, v164
	v_add_u32_e32 v167, 0x11000, v164
	v_add_u32_e32 v168, 0x13000, v164
	v_add_u32_e32 v169, 0x21000, v164
	v_add_u32_e32 v170, 0x23000, v164
	v_add_u32_e32 v171, 0x31000, v164
	v_add_u32_e32 v172, 0x33000, v164
	v_lshlrev_b32_e32 v115, 3, v180
	v_add_u32_e32 v115, 0x1e200000, v115
	v_mov_b32_e32 v223, s71
	v_mul_u32_u24_e32 v223, 3, v223
	v_add_u32_e32 v223, 0, v223
	v_lshl_add_u32 v208, v223, 12, v181
	global_load_dwordx2 v[132:133], v115, s[30:31] offset:0
	global_load_dwordx2 v[134:135], v115, s[30:31] offset:8
	global_load_dwordx2 v[136:137], v115, s[30:31] offset:16
	global_load_dwordx2 v[138:139], v115, s[30:31] offset:24
	global_load_dwordx2 v[140:141], v115, s[30:31] offset:128
	global_load_dwordx2 v[142:143], v115, s[30:31] offset:136
	global_load_dwordx2 v[144:145], v115, s[30:31] offset:144
	global_load_dwordx2 v[146:147], v115, s[30:31] offset:152
	global_load_dwordx2 v[148:149], v115, s[30:31] offset:256
	global_load_dwordx2 v[150:151], v115, s[30:31] offset:264
	global_load_dwordx2 v[152:153], v115, s[30:31] offset:272
	global_load_dwordx2 v[154:155], v115, s[30:31] offset:280
	global_load_dwordx2 v[156:157], v115, s[30:31] offset:384
	global_load_dwordx2 v[158:159], v115, s[30:31] offset:392
	global_load_dwordx2 v[160:161], v115, s[30:31] offset:400
	global_load_dwordx2 v[162:163], v115, s[30:31] offset:408
	global_load_dword v239, v208, s[24:25] offset:0
	global_load_dword v243, v208, s[26:27] offset:0
	global_load_dword v240, v208, s[24:25] offset:64
	global_load_dword v244, v208, s[26:27] offset:64
	global_load_dword v241, v208, s[24:25] offset:128
	global_load_dword v245, v208, s[26:27] offset:128
	global_load_dword v242, v208, s[24:25] offset:192
	global_load_dword v112, v208, s[26:27] offset:192
	global_load_dword v173, v[246:247], off offset:0
	global_load_dword v174, v[246:247], off offset:64
	global_load_dword v175, v[246:247], off offset:128
	global_load_dword v176, v[246:247], off offset:192
	global_load_dword v177, v165, s[28:29] offset:-4096
	global_load_dword v178, v165, s[28:29] offset:0
	global_load_dword v179, v166, s[28:29] offset:-4096
	global_load_dword v224, v166, s[28:29] offset:0
	global_load_dword v225, v167, s[28:29] offset:-4096
	global_load_dword v226, v167, s[28:29] offset:0
	global_load_dword v227, v168, s[28:29] offset:-4096
	global_load_dword v228, v168, s[28:29] offset:0
	global_load_dword v229, v169, s[28:29] offset:-4096
	global_load_dword v230, v169, s[28:29] offset:0
	global_load_dword v231, v170, s[28:29] offset:-4096
	global_load_dword v234, v170, s[28:29] offset:0
	global_load_dword v235, v171, s[28:29] offset:-4096
	global_load_dword v236, v171, s[28:29] offset:0
	global_load_dword v237, v172, s[28:29] offset:-4096
	global_load_dword v238, v172, s[28:29] offset:0
	s_waitcnt vmcnt(15)
	v_add_f32_e32 v173, 1.0, v173
	v_add_f32_e32 v174, 1.0, v174
	v_add_f32_e32 v175, 1.0, v175
	v_add_f32_e32 v176, 1.0, v176
	v_sub_f32_e32 v177, v177, v132
	v_mul_f32_e32 v177, v177, v133
	v_fma_f32 v177, v239, v177, v243
	v_mul_f32_e32 v0, v0, v173
	v_fmac_f32_e32 v0, 0x3fb504f3, v177
	global_load_dword v177, v165, s[28:29] offset:-4032
	global_store_dword v165, v0, s[28:29] offset:-4096
	s_waitcnt vmcnt(16)
	v_sub_f32_e32 v178, v178, v134
	v_mul_f32_e32 v178, v178, v135
	v_fma_f32 v178, v239, v178, v243
	v_mul_f32_e32 v1, v1, v173
	v_fmac_f32_e32 v1, 0x3fb504f3, v178
	global_load_dword v178, v165, s[28:29] offset:64
	global_store_dword v165, v1, s[28:29] offset:0
	s_waitcnt vmcnt(17)
	v_sub_f32_e32 v179, v179, v136
	v_mul_f32_e32 v179, v179, v137
	v_fma_f32 v179, v239, v179, v243
	v_mul_f32_e32 v2, v2, v173
	v_fmac_f32_e32 v2, 0x3fb504f3, v179
	global_load_dword v179, v166, s[28:29] offset:-4032
	global_store_dword v166, v2, s[28:29] offset:-4096
	s_waitcnt vmcnt(18)
	v_sub_f32_e32 v224, v224, v138
	v_mul_f32_e32 v224, v224, v139
	v_fma_f32 v224, v239, v224, v243
	v_mul_f32_e32 v3, v3, v173
	v_fmac_f32_e32 v3, 0x3fb504f3, v224
	global_load_dword v224, v166, s[28:29] offset:64
	global_store_dword v166, v3, s[28:29] offset:0
	s_waitcnt vmcnt(19)
	v_sub_f32_e32 v225, v225, v140
	v_mul_f32_e32 v225, v225, v141
	v_fma_f32 v225, v239, v225, v243
	v_mul_f32_e32 v16, v16, v173
	v_fmac_f32_e32 v16, 0x3fb504f3, v225
	global_load_dword v225, v167, s[28:29] offset:-4032
	global_store_dword v167, v16, s[28:29] offset:-4096
	s_waitcnt vmcnt(20)
	v_sub_f32_e32 v226, v226, v142
	v_mul_f32_e32 v226, v226, v143
	v_fma_f32 v226, v239, v226, v243
	v_mul_f32_e32 v17, v17, v173
	v_fmac_f32_e32 v17, 0x3fb504f3, v226
	global_load_dword v226, v167, s[28:29] offset:64
	global_store_dword v167, v17, s[28:29] offset:0
	s_waitcnt vmcnt(21)
	v_sub_f32_e32 v227, v227, v144
	v_mul_f32_e32 v227, v227, v145
	v_fma_f32 v227, v239, v227, v243
	v_mul_f32_e32 v18, v18, v173
	v_fmac_f32_e32 v18, 0x3fb504f3, v227
	global_load_dword v227, v168, s[28:29] offset:-4032
	global_store_dword v168, v18, s[28:29] offset:-4096
	s_waitcnt vmcnt(22)
	v_sub_f32_e32 v228, v228, v146
	v_mul_f32_e32 v228, v228, v147
	v_fma_f32 v228, v239, v228, v243
	v_mul_f32_e32 v19, v19, v173
	v_fmac_f32_e32 v19, 0x3fb504f3, v228
	global_load_dword v228, v168, s[28:29] offset:64
	global_store_dword v168, v19, s[28:29] offset:0
	s_waitcnt vmcnt(23)
	v_sub_f32_e32 v229, v229, v148
	v_mul_f32_e32 v229, v229, v149
	v_fma_f32 v229, v239, v229, v243
	v_mul_f32_e32 v32, v32, v173
	v_fmac_f32_e32 v32, 0x3fb504f3, v229
	global_load_dword v229, v169, s[28:29] offset:-4032
	global_store_dword v169, v32, s[28:29] offset:-4096
	s_waitcnt vmcnt(24)
	v_sub_f32_e32 v230, v230, v150
	v_mul_f32_e32 v230, v230, v151
	v_fma_f32 v230, v239, v230, v243
	v_mul_f32_e32 v33, v33, v173
	v_fmac_f32_e32 v33, 0x3fb504f3, v230
	global_load_dword v230, v169, s[28:29] offset:64
	global_store_dword v169, v33, s[28:29] offset:0
	s_waitcnt vmcnt(25)
	v_sub_f32_e32 v231, v231, v152
	v_mul_f32_e32 v231, v231, v153
	v_fma_f32 v231, v239, v231, v243
	v_mul_f32_e32 v34, v34, v173
	v_fmac_f32_e32 v34, 0x3fb504f3, v231
	global_load_dword v231, v170, s[28:29] offset:-4032
	global_store_dword v170, v34, s[28:29] offset:-4096
	s_waitcnt vmcnt(26)
	v_sub_f32_e32 v234, v234, v154
	v_mul_f32_e32 v234, v234, v155
	v_fma_f32 v234, v239, v234, v243
	v_mul_f32_e32 v35, v35, v173
	v_fmac_f32_e32 v35, 0x3fb504f3, v234
	global_load_dword v234, v170, s[28:29] offset:64
	global_store_dword v170, v35, s[28:29] offset:0
	s_waitcnt vmcnt(27)
	v_sub_f32_e32 v235, v235, v156
	v_mul_f32_e32 v235, v235, v157
	v_fma_f32 v235, v239, v235, v243
	v_mul_f32_e32 v48, v48, v173
	v_fmac_f32_e32 v48, 0x3fb504f3, v235
	global_load_dword v235, v171, s[28:29] offset:-4032
	global_store_dword v171, v48, s[28:29] offset:-4096
	s_waitcnt vmcnt(28)
	v_sub_f32_e32 v236, v236, v158
	v_mul_f32_e32 v236, v236, v159
	v_fma_f32 v236, v239, v236, v243
	v_mul_f32_e32 v49, v49, v173
	v_fmac_f32_e32 v49, 0x3fb504f3, v236
	global_load_dword v236, v171, s[28:29] offset:64
	global_store_dword v171, v49, s[28:29] offset:0
	s_waitcnt vmcnt(29)
	v_sub_f32_e32 v237, v237, v160
	v_mul_f32_e32 v237, v237, v161
	v_fma_f32 v237, v239, v237, v243
	v_mul_f32_e32 v50, v50, v173
	v_fmac_f32_e32 v50, 0x3fb504f3, v237
	global_load_dword v237, v172, s[28:29] offset:-4032
	global_store_dword v172, v50, s[28:29] offset:-4096
	s_waitcnt vmcnt(30)
	v_sub_f32_e32 v238, v238, v162
	v_mul_f32_e32 v238, v238, v163
	v_fma_f32 v238, v239, v238, v243
	v_mul_f32_e32 v51, v51, v173
	v_fmac_f32_e32 v51, 0x3fb504f3, v238
	global_load_dword v238, v172, s[28:29] offset:64
	global_store_dword v172, v51, s[28:29] offset:0
	s_waitcnt vmcnt(31)
	v_sub_f32_e32 v177, v177, v132
	v_mul_f32_e32 v177, v177, v133
	v_fma_f32 v177, v240, v177, v244
	v_mul_f32_e32 v4, v4, v174
	v_fmac_f32_e32 v4, 0x3fb504f3, v177
	global_load_dword v177, v165, s[28:29] offset:-3968
	global_store_dword v165, v4, s[28:29] offset:-4032
	s_waitcnt vmcnt(31)
	v_sub_f32_e32 v178, v178, v134
	v_mul_f32_e32 v178, v178, v135
	v_fma_f32 v178, v240, v178, v244
	v_mul_f32_e32 v5, v5, v174
	v_fmac_f32_e32 v5, 0x3fb504f3, v178
	global_load_dword v178, v165, s[28:29] offset:128
	global_store_dword v165, v5, s[28:29] offset:64
	s_waitcnt vmcnt(31)
	v_sub_f32_e32 v179, v179, v136
	v_mul_f32_e32 v179, v179, v137
	v_fma_f32 v179, v240, v179, v244
	v_mul_f32_e32 v6, v6, v174
	v_fmac_f32_e32 v6, 0x3fb504f3, v179
	global_load_dword v179, v166, s[28:29] offset:-3968
	global_store_dword v166, v6, s[28:29] offset:-4032
	s_waitcnt vmcnt(31)
	v_sub_f32_e32 v224, v224, v138
	v_mul_f32_e32 v224, v224, v139
	v_fma_f32 v224, v240, v224, v244
	v_mul_f32_e32 v7, v7, v174
	v_fmac_f32_e32 v7, 0x3fb504f3, v224
	global_load_dword v224, v166, s[28:29] offset:128
	global_store_dword v166, v7, s[28:29] offset:64
	s_waitcnt vmcnt(31)
	v_sub_f32_e32 v225, v225, v140
	v_mul_f32_e32 v225, v225, v141
	v_fma_f32 v225, v240, v225, v244
	v_mul_f32_e32 v20, v20, v174
	v_fmac_f32_e32 v20, 0x3fb504f3, v225
	global_load_dword v225, v167, s[28:29] offset:-3968
	global_store_dword v167, v20, s[28:29] offset:-4032
	s_waitcnt vmcnt(31)
	v_sub_f32_e32 v226, v226, v142
	v_mul_f32_e32 v226, v226, v143
	v_fma_f32 v226, v240, v226, v244
	v_mul_f32_e32 v21, v21, v174
	v_fmac_f32_e32 v21, 0x3fb504f3, v226
	global_load_dword v226, v167, s[28:29] offset:128
	global_store_dword v167, v21, s[28:29] offset:64
	s_waitcnt vmcnt(31)
	v_sub_f32_e32 v227, v227, v144
	v_mul_f32_e32 v227, v227, v145
	v_fma_f32 v227, v240, v227, v244
	v_mul_f32_e32 v22, v22, v174
	v_fmac_f32_e32 v22, 0x3fb504f3, v227
	global_load_dword v227, v168, s[28:29] offset:-3968
	global_store_dword v168, v22, s[28:29] offset:-4032
	s_waitcnt vmcnt(31)
	v_sub_f32_e32 v228, v228, v146
	v_mul_f32_e32 v228, v228, v147
	v_fma_f32 v228, v240, v228, v244
	v_mul_f32_e32 v23, v23, v174
	v_fmac_f32_e32 v23, 0x3fb504f3, v228
	global_load_dword v228, v168, s[28:29] offset:128
	global_store_dword v168, v23, s[28:29] offset:64
	s_waitcnt vmcnt(31)
	v_sub_f32_e32 v229, v229, v148
	v_mul_f32_e32 v229, v229, v149
	v_fma_f32 v229, v240, v229, v244
	v_mul_f32_e32 v36, v36, v174
	v_fmac_f32_e32 v36, 0x3fb504f3, v229
	global_load_dword v229, v169, s[28:29] offset:-3968
	global_store_dword v169, v36, s[28:29] offset:-4032
	s_waitcnt vmcnt(31)
	v_sub_f32_e32 v230, v230, v150
	v_mul_f32_e32 v230, v230, v151
	v_fma_f32 v230, v240, v230, v244
	v_mul_f32_e32 v37, v37, v174
	v_fmac_f32_e32 v37, 0x3fb504f3, v230
	global_load_dword v230, v169, s[28:29] offset:128
	global_store_dword v169, v37, s[28:29] offset:64
	s_waitcnt vmcnt(31)
	v_sub_f32_e32 v231, v231, v152
	v_mul_f32_e32 v231, v231, v153
	v_fma_f32 v231, v240, v231, v244
	v_mul_f32_e32 v38, v38, v174
	v_fmac_f32_e32 v38, 0x3fb504f3, v231
	global_load_dword v231, v170, s[28:29] offset:-3968
	global_store_dword v170, v38, s[28:29] offset:-4032
	s_waitcnt vmcnt(31)
	v_sub_f32_e32 v234, v234, v154
	v_mul_f32_e32 v234, v234, v155
	v_fma_f32 v234, v240, v234, v244
	v_mul_f32_e32 v39, v39, v174
	v_fmac_f32_e32 v39, 0x3fb504f3, v234
	global_load_dword v234, v170, s[28:29] offset:128
	global_store_dword v170, v39, s[28:29] offset:64
	s_waitcnt vmcnt(31)
	v_sub_f32_e32 v235, v235, v156
	v_mul_f32_e32 v235, v235, v157
	v_fma_f32 v235, v240, v235, v244
	v_mul_f32_e32 v52, v52, v174
	v_fmac_f32_e32 v52, 0x3fb504f3, v235
	global_load_dword v235, v171, s[28:29] offset:-3968
	global_store_dword v171, v52, s[28:29] offset:-4032
	s_waitcnt vmcnt(31)
	v_sub_f32_e32 v236, v236, v158
	v_mul_f32_e32 v236, v236, v159
	v_fma_f32 v236, v240, v236, v244
	v_mul_f32_e32 v53, v53, v174
	v_fmac_f32_e32 v53, 0x3fb504f3, v236
	global_load_dword v236, v171, s[28:29] offset:128
	global_store_dword v171, v53, s[28:29] offset:64
	s_waitcnt vmcnt(31)
	v_sub_f32_e32 v237, v237, v160
	v_mul_f32_e32 v237, v237, v161
	v_fma_f32 v237, v240, v237, v244
	v_mul_f32_e32 v54, v54, v174
	v_fmac_f32_e32 v54, 0x3fb504f3, v237
	global_load_dword v237, v172, s[28:29] offset:-3968
	global_store_dword v172, v54, s[28:29] offset:-4032
	s_waitcnt vmcnt(31)
	v_sub_f32_e32 v238, v238, v162
	v_mul_f32_e32 v238, v238, v163
	v_fma_f32 v238, v240, v238, v244
	v_mul_f32_e32 v55, v55, v174
	v_fmac_f32_e32 v55, 0x3fb504f3, v238
	global_load_dword v238, v172, s[28:29] offset:128
	global_store_dword v172, v55, s[28:29] offset:64
	s_waitcnt vmcnt(31)
	v_sub_f32_e32 v177, v177, v132
	v_mul_f32_e32 v177, v177, v133
	v_fma_f32 v177, v241, v177, v245
	v_mul_f32_e32 v8, v8, v175
	v_fmac_f32_e32 v8, 0x3fb504f3, v177
	global_load_dword v177, v165, s[28:29] offset:-3904
	global_store_dword v165, v8, s[28:29] offset:-3968
	s_waitcnt vmcnt(31)
	v_sub_f32_e32 v178, v178, v134
	v_mul_f32_e32 v178, v178, v135
	v_fma_f32 v178, v241, v178, v245
	v_mul_f32_e32 v9, v9, v175
	v_fmac_f32_e32 v9, 0x3fb504f3, v178
	global_load_dword v178, v165, s[28:29] offset:192
	global_store_dword v165, v9, s[28:29] offset:128
	s_waitcnt vmcnt(31)
	v_sub_f32_e32 v179, v179, v136
	v_mul_f32_e32 v179, v179, v137
	v_fma_f32 v179, v241, v179, v245
	v_mul_f32_e32 v10, v10, v175
	v_fmac_f32_e32 v10, 0x3fb504f3, v179
	global_load_dword v179, v166, s[28:29] offset:-3904
	global_store_dword v166, v10, s[28:29] offset:-3968
	s_waitcnt vmcnt(31)
	v_sub_f32_e32 v224, v224, v138
	v_mul_f32_e32 v224, v224, v139
	v_fma_f32 v224, v241, v224, v245
	v_mul_f32_e32 v11, v11, v175
	v_fmac_f32_e32 v11, 0x3fb504f3, v224
	global_load_dword v224, v166, s[28:29] offset:192
	global_store_dword v166, v11, s[28:29] offset:128
	s_waitcnt vmcnt(31)
	v_sub_f32_e32 v225, v225, v140
	v_mul_f32_e32 v225, v225, v141
	v_fma_f32 v225, v241, v225, v245
	v_mul_f32_e32 v24, v24, v175
	v_fmac_f32_e32 v24, 0x3fb504f3, v225
	global_load_dword v225, v167, s[28:29] offset:-3904
	global_store_dword v167, v24, s[28:29] offset:-3968
	s_waitcnt vmcnt(31)
	v_sub_f32_e32 v226, v226, v142
	v_mul_f32_e32 v226, v226, v143
	v_fma_f32 v226, v241, v226, v245
	v_mul_f32_e32 v25, v25, v175
	v_fmac_f32_e32 v25, 0x3fb504f3, v226
	global_load_dword v226, v167, s[28:29] offset:192
	global_store_dword v167, v25, s[28:29] offset:128
	s_waitcnt vmcnt(31)
	v_sub_f32_e32 v227, v227, v144
	v_mul_f32_e32 v227, v227, v145
	v_fma_f32 v227, v241, v227, v245
	v_mul_f32_e32 v26, v26, v175
	v_fmac_f32_e32 v26, 0x3fb504f3, v227
	global_load_dword v227, v168, s[28:29] offset:-3904
	global_store_dword v168, v26, s[28:29] offset:-3968
	s_waitcnt vmcnt(31)
	v_sub_f32_e32 v228, v228, v146
	v_mul_f32_e32 v228, v228, v147
	v_fma_f32 v228, v241, v228, v245
	v_mul_f32_e32 v27, v27, v175
	v_fmac_f32_e32 v27, 0x3fb504f3, v228
	global_load_dword v228, v168, s[28:29] offset:192
	global_store_dword v168, v27, s[28:29] offset:128
	s_waitcnt vmcnt(31)
	v_sub_f32_e32 v229, v229, v148
	v_mul_f32_e32 v229, v229, v149
	v_fma_f32 v229, v241, v229, v245
	v_mul_f32_e32 v40, v40, v175
	v_fmac_f32_e32 v40, 0x3fb504f3, v229
	global_load_dword v229, v169, s[28:29] offset:-3904
	global_store_dword v169, v40, s[28:29] offset:-3968
	s_waitcnt vmcnt(31)
	v_sub_f32_e32 v230, v230, v150
	v_mul_f32_e32 v230, v230, v151
	v_fma_f32 v230, v241, v230, v245
	v_mul_f32_e32 v41, v41, v175
	v_fmac_f32_e32 v41, 0x3fb504f3, v230
	global_load_dword v230, v169, s[28:29] offset:192
	global_store_dword v169, v41, s[28:29] offset:128
	s_waitcnt vmcnt(31)
	v_sub_f32_e32 v231, v231, v152
	v_mul_f32_e32 v231, v231, v153
	v_fma_f32 v231, v241, v231, v245
	v_mul_f32_e32 v42, v42, v175
	v_fmac_f32_e32 v42, 0x3fb504f3, v231
	global_load_dword v231, v170, s[28:29] offset:-3904
	global_store_dword v170, v42, s[28:29] offset:-3968
	s_waitcnt vmcnt(31)
	v_sub_f32_e32 v234, v234, v154
	v_mul_f32_e32 v234, v234, v155
	v_fma_f32 v234, v241, v234, v245
	v_mul_f32_e32 v43, v43, v175
	v_fmac_f32_e32 v43, 0x3fb504f3, v234
	global_load_dword v234, v170, s[28:29] offset:192
	global_store_dword v170, v43, s[28:29] offset:128
	s_waitcnt vmcnt(31)
	v_sub_f32_e32 v235, v235, v156
	v_mul_f32_e32 v235, v235, v157
	v_fma_f32 v235, v241, v235, v245
	v_mul_f32_e32 v56, v56, v175
	v_fmac_f32_e32 v56, 0x3fb504f3, v235
	global_load_dword v235, v171, s[28:29] offset:-3904
	global_store_dword v171, v56, s[28:29] offset:-3968
	s_waitcnt vmcnt(31)
	v_sub_f32_e32 v236, v236, v158
	v_mul_f32_e32 v236, v236, v159
	v_fma_f32 v236, v241, v236, v245
	v_mul_f32_e32 v57, v57, v175
	v_fmac_f32_e32 v57, 0x3fb504f3, v236
	global_load_dword v236, v171, s[28:29] offset:192
	global_store_dword v171, v57, s[28:29] offset:128
	s_waitcnt vmcnt(31)
	v_sub_f32_e32 v237, v237, v160
	v_mul_f32_e32 v237, v237, v161
	v_fma_f32 v237, v241, v237, v245
	v_mul_f32_e32 v58, v58, v175
	v_fmac_f32_e32 v58, 0x3fb504f3, v237
	global_load_dword v237, v172, s[28:29] offset:-3904
	global_store_dword v172, v58, s[28:29] offset:-3968
	s_waitcnt vmcnt(31)
	v_sub_f32_e32 v238, v238, v162
	v_mul_f32_e32 v238, v238, v163
	v_fma_f32 v238, v241, v238, v245
	v_mul_f32_e32 v59, v59, v175
	v_fmac_f32_e32 v59, 0x3fb504f3, v238
	global_load_dword v238, v172, s[28:29] offset:192
	global_store_dword v172, v59, s[28:29] offset:128
	s_waitcnt vmcnt(31)
	v_sub_f32_e32 v177, v177, v132
	v_mul_f32_e32 v177, v177, v133
	v_fma_f32 v177, v242, v177, v112
	v_mul_f32_e32 v12, v12, v176
	v_fmac_f32_e32 v12, 0x3fb504f3, v177
	global_store_dword v165, v12, s[28:29] offset:-3904
	s_waitcnt vmcnt(30)
	v_sub_f32_e32 v178, v178, v134
	v_mul_f32_e32 v178, v178, v135
	v_fma_f32 v178, v242, v178, v112
	v_mul_f32_e32 v13, v13, v176
	v_fmac_f32_e32 v13, 0x3fb504f3, v178
	global_store_dword v165, v13, s[28:29] offset:192
	s_waitcnt vmcnt(29)
	v_sub_f32_e32 v179, v179, v136
	v_mul_f32_e32 v179, v179, v137
	v_fma_f32 v179, v242, v179, v112
	v_mul_f32_e32 v14, v14, v176
	v_fmac_f32_e32 v14, 0x3fb504f3, v179
	global_store_dword v166, v14, s[28:29] offset:-3904
	s_waitcnt vmcnt(28)
	v_sub_f32_e32 v224, v224, v138
	v_mul_f32_e32 v224, v224, v139
	v_fma_f32 v224, v242, v224, v112
	v_mul_f32_e32 v15, v15, v176
	v_fmac_f32_e32 v15, 0x3fb504f3, v224
	global_store_dword v166, v15, s[28:29] offset:192
	s_waitcnt vmcnt(27)
	v_sub_f32_e32 v225, v225, v140
	v_mul_f32_e32 v225, v225, v141
	v_fma_f32 v225, v242, v225, v112
	v_mul_f32_e32 v28, v28, v176
	v_fmac_f32_e32 v28, 0x3fb504f3, v225
	global_store_dword v167, v28, s[28:29] offset:-3904
	s_waitcnt vmcnt(26)
	v_sub_f32_e32 v226, v226, v142
	v_mul_f32_e32 v226, v226, v143
	v_fma_f32 v226, v242, v226, v112
	v_mul_f32_e32 v29, v29, v176
	v_fmac_f32_e32 v29, 0x3fb504f3, v226
	global_store_dword v167, v29, s[28:29] offset:192
	s_waitcnt vmcnt(25)
	v_sub_f32_e32 v227, v227, v144
	v_mul_f32_e32 v227, v227, v145
	v_fma_f32 v227, v242, v227, v112
	v_mul_f32_e32 v30, v30, v176
	v_fmac_f32_e32 v30, 0x3fb504f3, v227
	global_store_dword v168, v30, s[28:29] offset:-3904
	s_waitcnt vmcnt(24)
	v_sub_f32_e32 v228, v228, v146
	v_mul_f32_e32 v228, v228, v147
	v_fma_f32 v228, v242, v228, v112
	v_mul_f32_e32 v31, v31, v176
	v_fmac_f32_e32 v31, 0x3fb504f3, v228
	global_store_dword v168, v31, s[28:29] offset:192
	s_waitcnt vmcnt(23)
	v_sub_f32_e32 v229, v229, v148
	v_mul_f32_e32 v229, v229, v149
	v_fma_f32 v229, v242, v229, v112
	v_mul_f32_e32 v44, v44, v176
	v_fmac_f32_e32 v44, 0x3fb504f3, v229
	global_store_dword v169, v44, s[28:29] offset:-3904
	s_waitcnt vmcnt(22)
	v_sub_f32_e32 v230, v230, v150
	v_mul_f32_e32 v230, v230, v151
	v_fma_f32 v230, v242, v230, v112
	v_mul_f32_e32 v45, v45, v176
	v_fmac_f32_e32 v45, 0x3fb504f3, v230
	global_store_dword v169, v45, s[28:29] offset:192
	s_waitcnt vmcnt(21)
	v_sub_f32_e32 v231, v231, v152
	v_mul_f32_e32 v231, v231, v153
	v_fma_f32 v231, v242, v231, v112
	v_mul_f32_e32 v46, v46, v176
	v_fmac_f32_e32 v46, 0x3fb504f3, v231
	global_store_dword v170, v46, s[28:29] offset:-3904
	s_waitcnt vmcnt(20)
	v_sub_f32_e32 v234, v234, v154
	v_mul_f32_e32 v234, v234, v155
	v_fma_f32 v234, v242, v234, v112
	v_mul_f32_e32 v47, v47, v176
	v_fmac_f32_e32 v47, 0x3fb504f3, v234
	global_store_dword v170, v47, s[28:29] offset:192
	s_waitcnt vmcnt(19)
	v_sub_f32_e32 v235, v235, v156
	v_mul_f32_e32 v235, v235, v157
	v_fma_f32 v235, v242, v235, v112
	v_mul_f32_e32 v60, v60, v176
	v_fmac_f32_e32 v60, 0x3fb504f3, v235
	global_store_dword v171, v60, s[28:29] offset:-3904
	s_waitcnt vmcnt(18)
	v_sub_f32_e32 v236, v236, v158
	v_mul_f32_e32 v236, v236, v159
	v_fma_f32 v236, v242, v236, v112
	v_mul_f32_e32 v61, v61, v176
	v_fmac_f32_e32 v61, 0x3fb504f3, v236
	global_store_dword v171, v61, s[28:29] offset:192
	s_waitcnt vmcnt(17)
	v_sub_f32_e32 v237, v237, v160
	v_mul_f32_e32 v237, v237, v161
	v_fma_f32 v237, v242, v237, v112
	v_mul_f32_e32 v62, v62, v176
	v_fmac_f32_e32 v62, 0x3fb504f3, v237
	global_store_dword v172, v62, s[28:29] offset:-3904
	s_waitcnt vmcnt(16)
	v_sub_f32_e32 v238, v238, v162
	v_mul_f32_e32 v238, v238, v163
	v_fma_f32 v238, v242, v238, v112
	v_mul_f32_e32 v63, v63, v176
	v_fmac_f32_e32 v63, 0x3fb504f3, v238
	global_store_dword v172, v63, s[28:29] offset:192
	v_add_u32_e32 v180, 64, v180
	v_lshl_add_u32 v164, v180, 12, v181
	v_add_u32_e32 v165, 0x1000, v164
	v_add_u32_e32 v166, 0x3000, v164
	v_add_u32_e32 v167, 0x11000, v164
	v_add_u32_e32 v168, 0x13000, v164
	v_add_u32_e32 v169, 0x21000, v164
	v_add_u32_e32 v170, 0x23000, v164
	v_add_u32_e32 v171, 0x31000, v164
	v_add_u32_e32 v172, 0x33000, v164
	v_lshlrev_b32_e32 v35, 3, v180
	v_add_u32_e32 v35, 0x1e200000, v35
	v_mov_b32_e32 v49, s71
	v_mul_u32_u24_e32 v49, 3, v49
	v_add_u32_e32 v49, 0, v49
	v_lshl_add_u32 v48, v49, 12, v181
	global_load_dwordx2 v[132:133], v35, s[30:31] offset:0
	global_load_dwordx2 v[134:135], v35, s[30:31] offset:8
	global_load_dwordx2 v[136:137], v35, s[30:31] offset:16
	global_load_dwordx2 v[138:139], v35, s[30:31] offset:24
	global_load_dwordx2 v[140:141], v35, s[30:31] offset:128
	global_load_dwordx2 v[142:143], v35, s[30:31] offset:136
	global_load_dwordx2 v[144:145], v35, s[30:31] offset:144
	global_load_dwordx2 v[146:147], v35, s[30:31] offset:152
	global_load_dwordx2 v[148:149], v35, s[30:31] offset:256
	global_load_dwordx2 v[150:151], v35, s[30:31] offset:264
	global_load_dwordx2 v[152:153], v35, s[30:31] offset:272
	global_load_dwordx2 v[154:155], v35, s[30:31] offset:280
	global_load_dwordx2 v[156:157], v35, s[30:31] offset:384
	global_load_dwordx2 v[158:159], v35, s[30:31] offset:392
	global_load_dwordx2 v[160:161], v35, s[30:31] offset:400
	global_load_dwordx2 v[162:163], v35, s[30:31] offset:408
	global_load_dword v3, v48, s[24:25] offset:0
	global_load_dword v19, v48, s[26:27] offset:0
	global_load_dword v16, v48, s[24:25] offset:64
	global_load_dword v32, v48, s[26:27] offset:64
	global_load_dword v17, v48, s[24:25] offset:128
	global_load_dword v33, v48, s[26:27] offset:128
	global_load_dword v18, v48, s[24:25] offset:192
	global_load_dword v34, v48, s[26:27] offset:192
	global_load_dword v173, v[246:247], off offset:0
	global_load_dword v174, v[246:247], off offset:64
	global_load_dword v175, v[246:247], off offset:128
	global_load_dword v176, v[246:247], off offset:192
	global_load_dword v177, v165, s[28:29] offset:-4096
	global_load_dword v178, v165, s[28:29] offset:0
	global_load_dword v179, v166, s[28:29] offset:-4096
	global_load_dword v224, v166, s[28:29] offset:0
	global_load_dword v225, v167, s[28:29] offset:-4096
	global_load_dword v226, v167, s[28:29] offset:0
	global_load_dword v227, v168, s[28:29] offset:-4096
	global_load_dword v228, v168, s[28:29] offset:0
	global_load_dword v229, v169, s[28:29] offset:-4096
	global_load_dword v230, v169, s[28:29] offset:0
	global_load_dword v231, v170, s[28:29] offset:-4096
	global_load_dword v234, v170, s[28:29] offset:0
	global_load_dword v235, v171, s[28:29] offset:-4096
	global_load_dword v236, v171, s[28:29] offset:0
	global_load_dword v237, v172, s[28:29] offset:-4096
	global_load_dword v238, v172, s[28:29] offset:0
	global_load_dword v239, v165, s[28:29] offset:-4032
	global_load_dword v240, v165, s[28:29] offset:64
	global_load_dword v241, v166, s[28:29] offset:-4032
	global_load_dword v242, v166, s[28:29] offset:64
	global_load_dword v243, v167, s[28:29] offset:-4032
	global_load_dword v244, v167, s[28:29] offset:64
	global_load_dword v245, v168, s[28:29] offset:-4032
	global_load_dword v112, v168, s[28:29] offset:64
	global_load_dword v115, v169, s[28:29] offset:-4032
	global_load_dword v208, v169, s[28:29] offset:64
	global_load_dword v223, v170, s[28:29] offset:-4032
	global_load_dword v233, v170, s[28:29] offset:64
	global_load_dword v248, v171, s[28:29] offset:-4032
	global_load_dword v0, v171, s[28:29] offset:64
	global_load_dword v1, v172, s[28:29] offset:-4032
	global_load_dword v2, v172, s[28:29] offset:64
	s_waitcnt vmcnt(31)
	v_add_f32_e32 v173, 1.0, v173
	v_add_f32_e32 v174, 1.0, v174
	v_add_f32_e32 v175, 1.0, v175
	v_add_f32_e32 v176, 1.0, v176
	v_sub_f32_e32 v177, v177, v132
	v_mul_f32_e32 v177, v177, v133
	v_fma_f32 v177, v3, v177, v19
	v_mul_f32_e32 v64, v64, v173
	v_fmac_f32_e32 v64, 0x3fb504f3, v177
	global_load_dword v177, v165, s[28:29] offset:-3968
	global_store_dword v165, v64, s[28:29] offset:-4096
	s_waitcnt vmcnt(32)
	v_sub_f32_e32 v178, v178, v134
	v_mul_f32_e32 v178, v178, v135
	v_fma_f32 v178, v3, v178, v19
	v_mul_f32_e32 v65, v65, v173
	v_fmac_f32_e32 v65, 0x3fb504f3, v178
	global_load_dword v178, v165, s[28:29] offset:128
	global_store_dword v165, v65, s[28:29] offset:0
	s_waitcnt vmcnt(33)
	v_sub_f32_e32 v179, v179, v136
	v_mul_f32_e32 v179, v179, v137
	v_fma_f32 v179, v3, v179, v19
	v_mul_f32_e32 v66, v66, v173
	v_fmac_f32_e32 v66, 0x3fb504f3, v179
	global_load_dword v179, v166, s[28:29] offset:-3968
	global_store_dword v166, v66, s[28:29] offset:-4096
	s_waitcnt vmcnt(34)
	v_sub_f32_e32 v224, v224, v138
	v_mul_f32_e32 v224, v224, v139
	v_fma_f32 v224, v3, v224, v19
	v_mul_f32_e32 v67, v67, v173
	v_fmac_f32_e32 v67, 0x3fb504f3, v224
	global_load_dword v224, v166, s[28:29] offset:128
	global_store_dword v166, v67, s[28:29] offset:0
	s_waitcnt vmcnt(35)
	v_sub_f32_e32 v225, v225, v140
	v_mul_f32_e32 v225, v225, v141
	v_fma_f32 v225, v3, v225, v19
	v_mul_f32_e32 v80, v80, v173
	v_fmac_f32_e32 v80, 0x3fb504f3, v225
	global_load_dword v225, v167, s[28:29] offset:-3968
	global_store_dword v167, v80, s[28:29] offset:-4096
	s_waitcnt vmcnt(36)
	v_sub_f32_e32 v226, v226, v142
	v_mul_f32_e32 v226, v226, v143
	v_fma_f32 v226, v3, v226, v19
	v_mul_f32_e32 v81, v81, v173
	v_fmac_f32_e32 v81, 0x3fb504f3, v226
	global_load_dword v226, v167, s[28:29] offset:128
	global_store_dword v167, v81, s[28:29] offset:0
	s_waitcnt vmcnt(37)
	v_sub_f32_e32 v227, v227, v144
	v_mul_f32_e32 v227, v227, v145
	v_fma_f32 v227, v3, v227, v19
	v_mul_f32_e32 v82, v82, v173
	v_fmac_f32_e32 v82, 0x3fb504f3, v227
	global_load_dword v227, v168, s[28:29] offset:-3968
	global_store_dword v168, v82, s[28:29] offset:-4096
	s_waitcnt vmcnt(38)
	v_sub_f32_e32 v228, v228, v146
	v_mul_f32_e32 v228, v228, v147
	v_fma_f32 v228, v3, v228, v19
	v_mul_f32_e32 v83, v83, v173
	v_fmac_f32_e32 v83, 0x3fb504f3, v228
	global_load_dword v228, v168, s[28:29] offset:128
	global_store_dword v168, v83, s[28:29] offset:0
	s_waitcnt vmcnt(39)
	v_sub_f32_e32 v229, v229, v148
	v_mul_f32_e32 v229, v229, v149
	v_fma_f32 v229, v3, v229, v19
	v_mul_f32_e32 v96, v96, v173
	v_fmac_f32_e32 v96, 0x3fb504f3, v229
	global_load_dword v229, v169, s[28:29] offset:-3968
	global_store_dword v169, v96, s[28:29] offset:-4096
	s_waitcnt vmcnt(40)
	v_sub_f32_e32 v230, v230, v150
	v_mul_f32_e32 v230, v230, v151
	v_fma_f32 v230, v3, v230, v19
	v_mul_f32_e32 v97, v97, v173
	v_fmac_f32_e32 v97, 0x3fb504f3, v230
	global_load_dword v230, v169, s[28:29] offset:128
	global_store_dword v169, v97, s[28:29] offset:0
	s_waitcnt vmcnt(41)
	v_sub_f32_e32 v231, v231, v152
	v_mul_f32_e32 v231, v231, v153
	v_fma_f32 v231, v3, v231, v19
	v_mul_f32_e32 v98, v98, v173
	v_fmac_f32_e32 v98, 0x3fb504f3, v231
	global_load_dword v231, v170, s[28:29] offset:-3968
	global_store_dword v170, v98, s[28:29] offset:-4096
	s_waitcnt vmcnt(42)
	v_sub_f32_e32 v234, v234, v154
	v_mul_f32_e32 v234, v234, v155
	v_fma_f32 v234, v3, v234, v19
	v_mul_f32_e32 v99, v99, v173
	v_fmac_f32_e32 v99, 0x3fb504f3, v234
	global_load_dword v234, v170, s[28:29] offset:128
	global_store_dword v170, v99, s[28:29] offset:0
	s_waitcnt vmcnt(43)
	v_sub_f32_e32 v235, v235, v156
	v_mul_f32_e32 v235, v235, v157
	v_fma_f32 v235, v3, v235, v19
	v_mul_f32_e32 v116, v116, v173
	v_fmac_f32_e32 v116, 0x3fb504f3, v235
	global_load_dword v235, v171, s[28:29] offset:-3968
	global_store_dword v171, v116, s[28:29] offset:-4096
	s_waitcnt vmcnt(44)
	v_sub_f32_e32 v236, v236, v158
	v_mul_f32_e32 v236, v236, v159
	v_fma_f32 v236, v3, v236, v19
	v_mul_f32_e32 v117, v117, v173
	v_fmac_f32_e32 v117, 0x3fb504f3, v236
	global_load_dword v236, v171, s[28:29] offset:128
	global_store_dword v171, v117, s[28:29] offset:0
	s_waitcnt vmcnt(45)
	v_sub_f32_e32 v237, v237, v160
	v_mul_f32_e32 v237, v237, v161
	v_fma_f32 v237, v3, v237, v19
	v_mul_f32_e32 v118, v118, v173
	v_fmac_f32_e32 v118, 0x3fb504f3, v237
	global_load_dword v237, v172, s[28:29] offset:-3968
	global_store_dword v172, v118, s[28:29] offset:-4096
	s_waitcnt vmcnt(46)
	v_sub_f32_e32 v238, v238, v162
	v_mul_f32_e32 v238, v238, v163
	v_fma_f32 v238, v3, v238, v19
	v_mul_f32_e32 v119, v119, v173
	v_fmac_f32_e32 v119, 0x3fb504f3, v238
	global_load_dword v238, v172, s[28:29] offset:128
	global_store_dword v172, v119, s[28:29] offset:0
	s_waitcnt vmcnt(47)
	v_sub_f32_e32 v239, v239, v132
	v_mul_f32_e32 v239, v239, v133
	v_fma_f32 v239, v16, v239, v32
	v_mul_f32_e32 v68, v68, v174
	v_fmac_f32_e32 v68, 0x3fb504f3, v239
	global_load_dword v239, v165, s[28:29] offset:-3904
	global_store_dword v165, v68, s[28:29] offset:-4032
	s_waitcnt vmcnt(48)
	v_sub_f32_e32 v240, v240, v134
	v_mul_f32_e32 v240, v240, v135
	v_fma_f32 v240, v16, v240, v32
	v_mul_f32_e32 v69, v69, v174
	v_fmac_f32_e32 v69, 0x3fb504f3, v240
	global_load_dword v240, v165, s[28:29] offset:192
	global_store_dword v165, v69, s[28:29] offset:64
	s_waitcnt vmcnt(49)
	v_sub_f32_e32 v241, v241, v136
	v_mul_f32_e32 v241, v241, v137
	v_fma_f32 v241, v16, v241, v32
	v_mul_f32_e32 v70, v70, v174
	v_fmac_f32_e32 v70, 0x3fb504f3, v241
	global_load_dword v241, v166, s[28:29] offset:-3904
	global_store_dword v166, v70, s[28:29] offset:-4032
	s_waitcnt vmcnt(50)
	v_sub_f32_e32 v242, v242, v138
	v_mul_f32_e32 v242, v242, v139
	v_fma_f32 v242, v16, v242, v32
	v_mul_f32_e32 v71, v71, v174
	v_fmac_f32_e32 v71, 0x3fb504f3, v242
	global_load_dword v242, v166, s[28:29] offset:192
	global_store_dword v166, v71, s[28:29] offset:64
	s_waitcnt vmcnt(51)
	v_sub_f32_e32 v243, v243, v140
	v_mul_f32_e32 v243, v243, v141
	v_fma_f32 v243, v16, v243, v32
	v_mul_f32_e32 v84, v84, v174
	v_fmac_f32_e32 v84, 0x3fb504f3, v243
	global_load_dword v243, v167, s[28:29] offset:-3904
	global_store_dword v167, v84, s[28:29] offset:-4032
	s_waitcnt vmcnt(52)
	v_sub_f32_e32 v244, v244, v142
	v_mul_f32_e32 v244, v244, v143
	v_fma_f32 v244, v16, v244, v32
	v_mul_f32_e32 v85, v85, v174
	v_fmac_f32_e32 v85, 0x3fb504f3, v244
	global_load_dword v244, v167, s[28:29] offset:192
	global_store_dword v167, v85, s[28:29] offset:64
	s_waitcnt vmcnt(53)
	v_sub_f32_e32 v245, v245, v144
	v_mul_f32_e32 v245, v245, v145
	v_fma_f32 v245, v16, v245, v32
	v_mul_f32_e32 v86, v86, v174
	v_fmac_f32_e32 v86, 0x3fb504f3, v245
	global_load_dword v245, v168, s[28:29] offset:-3904
	global_store_dword v168, v86, s[28:29] offset:-4032
	s_waitcnt vmcnt(54)
	v_sub_f32_e32 v112, v112, v146
	v_mul_f32_e32 v112, v112, v147
	v_fma_f32 v112, v16, v112, v32
	v_mul_f32_e32 v87, v87, v174
	v_fmac_f32_e32 v87, 0x3fb504f3, v112
	global_load_dword v112, v168, s[28:29] offset:192
	global_store_dword v168, v87, s[28:29] offset:64
	s_waitcnt vmcnt(55)
	v_sub_f32_e32 v115, v115, v148
	v_mul_f32_e32 v115, v115, v149
	v_fma_f32 v115, v16, v115, v32
	v_mul_f32_e32 v100, v100, v174
	v_fmac_f32_e32 v100, 0x3fb504f3, v115
	global_load_dword v115, v169, s[28:29] offset:-3904
	global_store_dword v169, v100, s[28:29] offset:-4032
	s_waitcnt vmcnt(56)
	v_sub_f32_e32 v208, v208, v150
	v_mul_f32_e32 v208, v208, v151
	v_fma_f32 v208, v16, v208, v32
	v_mul_f32_e32 v101, v101, v174
	v_fmac_f32_e32 v101, 0x3fb504f3, v208
	global_load_dword v208, v169, s[28:29] offset:192
	global_store_dword v169, v101, s[28:29] offset:64
	s_waitcnt vmcnt(57)
	v_sub_f32_e32 v223, v223, v152
	v_mul_f32_e32 v223, v223, v153
	v_fma_f32 v223, v16, v223, v32
	v_mul_f32_e32 v102, v102, v174
	v_fmac_f32_e32 v102, 0x3fb504f3, v223
	global_load_dword v223, v170, s[28:29] offset:-3904
	global_store_dword v170, v102, s[28:29] offset:-4032
	s_waitcnt vmcnt(58)
	v_sub_f32_e32 v233, v233, v154
	v_mul_f32_e32 v233, v233, v155
	v_fma_f32 v233, v16, v233, v32
	v_mul_f32_e32 v103, v103, v174
	v_fmac_f32_e32 v103, 0x3fb504f3, v233
	global_load_dword v233, v170, s[28:29] offset:192
	global_store_dword v170, v103, s[28:29] offset:64
	s_waitcnt vmcnt(59)
	v_sub_f32_e32 v248, v248, v156
	v_mul_f32_e32 v248, v248, v157
	v_fma_f32 v248, v16, v248, v32
	v_mul_f32_e32 v120, v120, v174
	v_fmac_f32_e32 v120, 0x3fb504f3, v248
	global_load_dword v248, v171, s[28:29] offset:-3904
	global_store_dword v171, v120, s[28:29] offset:-4032
	s_waitcnt vmcnt(60)
	v_sub_f32_e32 v0, v0, v158
	v_mul_f32_e32 v0, v0, v159
	v_fma_f32 v0, v16, v0, v32
	v_mul_f32_e32 v121, v121, v174
	v_fmac_f32_e32 v121, 0x3fb504f3, v0
	global_load_dword v0, v171, s[28:29] offset:192
	global_store_dword v171, v121, s[28:29] offset:64
	s_waitcnt vmcnt(61)
	v_sub_f32_e32 v1, v1, v160
	v_mul_f32_e32 v1, v1, v161
	v_fma_f32 v1, v16, v1, v32
	v_mul_f32_e32 v122, v122, v174
	v_fmac_f32_e32 v122, 0x3fb504f3, v1
	global_load_dword v1, v172, s[28:29] offset:-3904
	global_store_dword v172, v122, s[28:29] offset:-4032
	s_waitcnt vmcnt(62)
	v_sub_f32_e32 v2, v2, v162
	v_mul_f32_e32 v2, v2, v163
	v_fma_f32 v2, v16, v2, v32
	v_mul_f32_e32 v123, v123, v174
	v_fmac_f32_e32 v123, 0x3fb504f3, v2
	global_load_dword v2, v172, s[28:29] offset:192
	global_store_dword v172, v123, s[28:29] offset:64
	s_waitcnt vmcnt(63)
	v_sub_f32_e32 v177, v177, v132
	v_mul_f32_e32 v177, v177, v133
	v_fma_f32 v177, v17, v177, v33
	v_mul_f32_e32 v72, v72, v175
	v_fmac_f32_e32 v72, 0x3fb504f3, v177
	global_store_dword v165, v72, s[28:29] offset:-3968
	s_waitcnt vmcnt(62)
	v_sub_f32_e32 v178, v178, v134
	v_mul_f32_e32 v178, v178, v135
	v_fma_f32 v178, v17, v178, v33
	v_mul_f32_e32 v73, v73, v175
	v_fmac_f32_e32 v73, 0x3fb504f3, v178
	global_store_dword v165, v73, s[28:29] offset:128
	s_waitcnt vmcnt(61)
	v_sub_f32_e32 v179, v179, v136
	v_mul_f32_e32 v179, v179, v137
	v_fma_f32 v179, v17, v179, v33
	v_mul_f32_e32 v74, v74, v175
	v_fmac_f32_e32 v74, 0x3fb504f3, v179
	global_store_dword v166, v74, s[28:29] offset:-3968
	s_waitcnt vmcnt(60)
	v_sub_f32_e32 v224, v224, v138
	v_mul_f32_e32 v224, v224, v139
	v_fma_f32 v224, v17, v224, v33
	v_mul_f32_e32 v75, v75, v175
	v_fmac_f32_e32 v75, 0x3fb504f3, v224
	global_store_dword v166, v75, s[28:29] offset:128
	s_waitcnt vmcnt(59)
	v_sub_f32_e32 v225, v225, v140
	v_mul_f32_e32 v225, v225, v141
	v_fma_f32 v225, v17, v225, v33
	v_mul_f32_e32 v88, v88, v175
	v_fmac_f32_e32 v88, 0x3fb504f3, v225
	global_store_dword v167, v88, s[28:29] offset:-3968
	s_waitcnt vmcnt(58)
	v_sub_f32_e32 v226, v226, v142
	v_mul_f32_e32 v226, v226, v143
	v_fma_f32 v226, v17, v226, v33
	v_mul_f32_e32 v89, v89, v175
	v_fmac_f32_e32 v89, 0x3fb504f3, v226
	global_store_dword v167, v89, s[28:29] offset:128
	s_waitcnt vmcnt(57)
	v_sub_f32_e32 v227, v227, v144
	v_mul_f32_e32 v227, v227, v145
	v_fma_f32 v227, v17, v227, v33
	v_mul_f32_e32 v90, v90, v175
	v_fmac_f32_e32 v90, 0x3fb504f3, v227
	global_store_dword v168, v90, s[28:29] offset:-3968
	s_waitcnt vmcnt(56)
	v_sub_f32_e32 v228, v228, v146
	v_mul_f32_e32 v228, v228, v147
	v_fma_f32 v228, v17, v228, v33
	v_mul_f32_e32 v91, v91, v175
	v_fmac_f32_e32 v91, 0x3fb504f3, v228
	global_store_dword v168, v91, s[28:29] offset:128
	s_waitcnt vmcnt(55)
	v_sub_f32_e32 v229, v229, v148
	v_mul_f32_e32 v229, v229, v149
	v_fma_f32 v229, v17, v229, v33
	v_mul_f32_e32 v104, v104, v175
	v_fmac_f32_e32 v104, 0x3fb504f3, v229
	global_store_dword v169, v104, s[28:29] offset:-3968
	s_waitcnt vmcnt(54)
	v_sub_f32_e32 v230, v230, v150
	v_mul_f32_e32 v230, v230, v151
	v_fma_f32 v230, v17, v230, v33
	v_mul_f32_e32 v105, v105, v175
	v_fmac_f32_e32 v105, 0x3fb504f3, v230
	global_store_dword v169, v105, s[28:29] offset:128
	s_waitcnt vmcnt(53)
	v_sub_f32_e32 v231, v231, v152
	v_mul_f32_e32 v231, v231, v153
	v_fma_f32 v231, v17, v231, v33
	v_mul_f32_e32 v106, v106, v175
	v_fmac_f32_e32 v106, 0x3fb504f3, v231
	global_store_dword v170, v106, s[28:29] offset:-3968
	s_waitcnt vmcnt(52)
	v_sub_f32_e32 v234, v234, v154
	v_mul_f32_e32 v234, v234, v155
	v_fma_f32 v234, v17, v234, v33
	v_mul_f32_e32 v107, v107, v175
	v_fmac_f32_e32 v107, 0x3fb504f3, v234
	global_store_dword v170, v107, s[28:29] offset:128
	s_waitcnt vmcnt(51)
	v_sub_f32_e32 v235, v235, v156
	v_mul_f32_e32 v235, v235, v157
	v_fma_f32 v235, v17, v235, v33
	v_mul_f32_e32 v124, v124, v175
	v_fmac_f32_e32 v124, 0x3fb504f3, v235
	global_store_dword v171, v124, s[28:29] offset:-3968
	s_waitcnt vmcnt(50)
	v_sub_f32_e32 v236, v236, v158
	v_mul_f32_e32 v236, v236, v159
	v_fma_f32 v236, v17, v236, v33
	v_mul_f32_e32 v125, v125, v175
	v_fmac_f32_e32 v125, 0x3fb504f3, v236
	global_store_dword v171, v125, s[28:29] offset:128
	s_waitcnt vmcnt(49)
	v_sub_f32_e32 v237, v237, v160
	v_mul_f32_e32 v237, v237, v161
	v_fma_f32 v237, v17, v237, v33
	v_mul_f32_e32 v126, v126, v175
	v_fmac_f32_e32 v126, 0x3fb504f3, v237
	global_store_dword v172, v126, s[28:29] offset:-3968
	s_waitcnt vmcnt(48)
	v_sub_f32_e32 v238, v238, v162
	v_mul_f32_e32 v238, v238, v163
	v_fma_f32 v238, v17, v238, v33
	v_mul_f32_e32 v127, v127, v175
	v_fmac_f32_e32 v127, 0x3fb504f3, v238
	global_store_dword v172, v127, s[28:29] offset:128
	s_waitcnt vmcnt(47)
	v_sub_f32_e32 v239, v239, v132
	v_mul_f32_e32 v239, v239, v133
	v_fma_f32 v239, v18, v239, v34
	v_mul_f32_e32 v76, v76, v176
	v_fmac_f32_e32 v76, 0x3fb504f3, v239
	global_store_dword v165, v76, s[28:29] offset:-3904
	s_waitcnt vmcnt(46)
	v_sub_f32_e32 v240, v240, v134
	v_mul_f32_e32 v240, v240, v135
	v_fma_f32 v240, v18, v240, v34
	v_mul_f32_e32 v77, v77, v176
	v_fmac_f32_e32 v77, 0x3fb504f3, v240
	global_store_dword v165, v77, s[28:29] offset:192
	s_waitcnt vmcnt(45)
	v_sub_f32_e32 v241, v241, v136
	v_mul_f32_e32 v241, v241, v137
	v_fma_f32 v241, v18, v241, v34
	v_mul_f32_e32 v78, v78, v176
	v_fmac_f32_e32 v78, 0x3fb504f3, v241
	global_store_dword v166, v78, s[28:29] offset:-3904
	s_waitcnt vmcnt(44)
	v_sub_f32_e32 v242, v242, v138
	v_mul_f32_e32 v242, v242, v139
	v_fma_f32 v242, v18, v242, v34
	v_mul_f32_e32 v79, v79, v176
	v_fmac_f32_e32 v79, 0x3fb504f3, v242
	global_store_dword v166, v79, s[28:29] offset:192
	s_waitcnt vmcnt(43)
	v_sub_f32_e32 v243, v243, v140
	v_mul_f32_e32 v243, v243, v141
	v_fma_f32 v243, v18, v243, v34
	v_mul_f32_e32 v92, v92, v176
	v_fmac_f32_e32 v92, 0x3fb504f3, v243
	global_store_dword v167, v92, s[28:29] offset:-3904
	s_waitcnt vmcnt(42)
	v_sub_f32_e32 v244, v244, v142
	v_mul_f32_e32 v244, v244, v143
	v_fma_f32 v244, v18, v244, v34
	v_mul_f32_e32 v93, v93, v176
	v_fmac_f32_e32 v93, 0x3fb504f3, v244
	global_store_dword v167, v93, s[28:29] offset:192
	s_waitcnt vmcnt(41)
	v_sub_f32_e32 v245, v245, v144
	v_mul_f32_e32 v245, v245, v145
	v_fma_f32 v245, v18, v245, v34
	v_mul_f32_e32 v94, v94, v176
	v_fmac_f32_e32 v94, 0x3fb504f3, v245
	global_store_dword v168, v94, s[28:29] offset:-3904
	s_waitcnt vmcnt(40)
	v_sub_f32_e32 v112, v112, v146
	v_mul_f32_e32 v112, v112, v147
	v_fma_f32 v112, v18, v112, v34
	v_mul_f32_e32 v95, v95, v176
	v_fmac_f32_e32 v95, 0x3fb504f3, v112
	global_store_dword v168, v95, s[28:29] offset:192
	s_waitcnt vmcnt(39)
	v_sub_f32_e32 v115, v115, v148
	v_mul_f32_e32 v115, v115, v149
	v_fma_f32 v115, v18, v115, v34
	v_mul_f32_e32 v108, v108, v176
	v_fmac_f32_e32 v108, 0x3fb504f3, v115
	global_store_dword v169, v108, s[28:29] offset:-3904
	s_waitcnt vmcnt(38)
	v_sub_f32_e32 v208, v208, v150
	v_mul_f32_e32 v208, v208, v151
	v_fma_f32 v208, v18, v208, v34
	v_mul_f32_e32 v109, v109, v176
	v_fmac_f32_e32 v109, 0x3fb504f3, v208
	global_store_dword v169, v109, s[28:29] offset:192
	s_waitcnt vmcnt(37)
	v_sub_f32_e32 v223, v223, v152
	v_mul_f32_e32 v223, v223, v153
	v_fma_f32 v223, v18, v223, v34
	v_mul_f32_e32 v110, v110, v176
	v_fmac_f32_e32 v110, 0x3fb504f3, v223
	global_store_dword v170, v110, s[28:29] offset:-3904
	s_waitcnt vmcnt(36)
	v_sub_f32_e32 v233, v233, v154
	v_mul_f32_e32 v233, v233, v155
	v_fma_f32 v233, v18, v233, v34
	v_mul_f32_e32 v111, v111, v176
	v_fmac_f32_e32 v111, 0x3fb504f3, v233
	global_store_dword v170, v111, s[28:29] offset:192
	s_waitcnt vmcnt(35)
	v_sub_f32_e32 v248, v248, v156
	v_mul_f32_e32 v248, v248, v157
	v_fma_f32 v248, v18, v248, v34
	v_mul_f32_e32 v128, v128, v176
	v_fmac_f32_e32 v128, 0x3fb504f3, v248
	global_store_dword v171, v128, s[28:29] offset:-3904
	s_waitcnt vmcnt(34)
	v_sub_f32_e32 v0, v0, v158
	v_mul_f32_e32 v0, v0, v159
	v_fma_f32 v0, v18, v0, v34
	v_mul_f32_e32 v129, v129, v176
	v_fmac_f32_e32 v129, 0x3fb504f3, v0
	global_store_dword v171, v129, s[28:29] offset:192
	s_waitcnt vmcnt(33)
	v_sub_f32_e32 v1, v1, v160
	v_mul_f32_e32 v1, v1, v161
	v_fma_f32 v1, v18, v1, v34
	v_mul_f32_e32 v130, v130, v176
	v_fmac_f32_e32 v130, 0x3fb504f3, v1
	global_store_dword v172, v130, s[28:29] offset:-3904
	s_waitcnt vmcnt(32)
	v_sub_f32_e32 v2, v2, v162
	v_mul_f32_e32 v2, v2, v163
	v_fma_f32 v2, v18, v2, v34
	v_mul_f32_e32 v131, v131, v176
	v_fmac_f32_e32 v131, 0x3fb504f3, v2
	global_store_dword v172, v131, s[28:29] offset:192
	s_add_i32 s11, s11, s59
	s_cmpk_gt_i32 s11, 0x3ff
	s_cbranch_scc0 .LBB0_600
	v_mov_b32_e32 v113, 0
	v_mov_b32_e32 v114, 0x3f317218
